# NSA compressed unit pass 2: first st=1 V fragment read hoisted next to the st=0 reads (one fewer on-demand read + wait per tile)
# baseline (speedup 1.0000x reference)
; DI unsigned pack2(float a, float b) { f32x2 v = {a, b}; bf16x2_t r = __builtin_convertvector(v, bf16x2_t); return __builtin_bit_cast(unsigned, r); }
; DI float bflo(unsigned v) { return __uint_as_float(v << 16); }
; DI float bfhi(unsigned v) { return __uint_as_float(v & 0xffff0000u); }
; DI f32x16 mfma32(bf16x8 a, bf16x8 b, f32x16 c) { return __builtin_amdgcn_mfma_f32_32x32x16_bf16(a, b, c, 0, 0, 0); }
; DI int crow(int i, int h) { return (i & 3) + 8 * (i >> 2) + 4 * h; }
; DI void nsa_cmp_unit(const Params& p, int u, char* smem) {
;     ...
;     for (int T = 0; T < ntile; ++T) {
;       f32x16 s;
; #pragma unroll
;       for (int i = 0; i < 16; ++i) s[i] = 0.f;
; #pragma unroll
;       for (int ks = 0; ks < 4; ++ks) s = mfma32(*(const bf16x8*)(Kc + (32 * T + r) * LSTR + 16 * ks + 8 * h), qf[ks], s);
; #pragma unroll
;       for (int i = 0; i < 16; ++i) { const bool valid = (32 * T + crow(i, h)) < nc; s[i] = valid ? __expf(s[i] - m) * inv : 0.f; }
; #pragma unroll
;       for (int st = 0; st < 2; ++st) {
;         u32x4 ph, pl;
; #pragma unroll
;         for (int e = 0; e < 4; ++e) {
;           const float a0 = s[8 * st + 2 * e], a1 = s[8 * st + 2 * e + 1];
;           const unsigned hw = pack2(a0, a1); ph[e] = hw; pl[e] = pack2(a0 - bflo(hw), a1 - bfhi(hw));
;         }
;         const bf16x8 pbh = __builtin_bit_cast(bf16x8, ph), pbl = __builtin_bit_cast(bf16x8, pl);
; #pragma unroll
;         for (int dt = 0; dt < 2; ++dt) {
;           const s16x4 lo = *(const s16x4*)(Vc + (32 * dt + r) * VSTR + 32 * T + 16 * st + 4 * h);
;           const s16x4 hi = *(const s16x4*)(Vc + (32 * dt + r) * VSTR + 32 * T + 16 * st + 8 + 4 * h);
;           o[dt] = mfma32(__builtin_shufflevector(lo, hi, 0, 1, 2, 3, 4, 5, 6, 7), pbh, o[dt]);
;         }
; #pragma unroll
;         for (int jt = 0; jt < 2; ++jt) {
;           if ((jt == 0 && T <= 3) || (jt == 1 && T >= 3)) {
;             const int base = 32 * T + 16 * st + 4 * h - 128 * jt - 4 * r;
;             bf16x8 ov;
; #pragma unroll
;             for (int jj = 0; jj < 8; ++jj) {
;               const int d = base + 8 * (jj >> 2) + (jj & 3);
;               ov[jj] = (short)((d == -1 || d == 3) ? 0x3F00 : ((d >= 0 && d <= 2) ? 0x3F80 : 0));
;             }
;             imp[jt] = mfma32(ov, pbh, imp[jt]);
;             imp[jt] = mfma32(ov, pbl, imp[jt]);
;           }
.LBB0_439:
	v_or_b32_e32 v152, 2, v0
	s_cmp_lt_u32 s33, 4
	s_cselect_b64 s[8:9], -1, 0
	s_waitcnt lgkmcnt(0)
	v_mfma_f32_32x32x16_bf16 v[66:81], v[234:237], v[102:105], 0
	v_add_u32_e32 v143, v132, v0
	v_mov_b32_e32 v117, v0
	v_mfma_f32_32x32x16_bf16 v[66:81], v[238:241], v[98:101], v[66:81]
	v_mfma_f32_32x32x16_bf16 v[66:81], v[242:245], v[106:109], v[66:81]
	v_add_u32_e32 v146, 1, v0
	v_cmp_lt_i32_e32 vcc, v146, v115
	v_or_b32_e32 v147, 3, v0
	v_mfma_f32_32x32x16_bf16 v[66:81], v[246:249], v[110:113], v[66:81]
	ds_read_b128 v[234:237], v141 offset:4608
	ds_read_b128 v[238:241], v141 offset:4640
	ds_read_b128 v[242:245], v141 offset:4672
	ds_read_b128 v[246:249], v141 offset:4704
	v_or_b32_e32 v150, 10, v0
	s_nop 10
	v_sub_f32_e32 v66, v66, v140
	v_sub_f32_e32 v67, v67, v140
	v_mul_f32_e32 v66, 0x3fb8aa3b, v66
	v_mul_f32_e32 v67, 0x3fb8aa3b, v67
	v_sub_f32_e32 v68, v68, v140
	v_sub_f32_e32 v69, v69, v140
	v_exp_f32_e32 v66, v66
	v_exp_f32_e32 v67, v67
	v_mul_f32_e32 v68, 0x3fb8aa3b, v68
	v_mul_f32_e32 v69, 0x3fb8aa3b, v69
	v_exp_f32_e32 v68, v68
	v_exp_f32_e32 v69, v69
	v_sub_f32_e32 v71, v71, v140
	v_sub_f32_e32 v70, v70, v140
	v_sub_f32_e32 v73, v73, v140
	v_mul_f32_e32 v71, 0x3fb8aa3b, v71
	v_pk_mul_f32 v[66:67], v[122:123], v[66:67]
	v_sub_f32_e32 v72, v72, v140
	v_mul_f32_e32 v70, 0x3fb8aa3b, v70
	v_mul_f32_e32 v145, 0x3fb8aa3b, v73
	v_exp_f32_e32 v73, v71
	v_cndmask_b32_e32 v71, 0, v67, vcc
	v_cmp_lt_i32_e32 vcc, v0, v116
	v_mul_f32_e32 v144, 0x3fb8aa3b, v72
	v_exp_f32_e32 v72, v70
	v_pk_mul_f32 v[68:69], v[122:123], v[68:69]
	v_cndmask_b32_e32 v70, 0, v66, vcc
	v_cmp_lt_i32_e32 vcc, v147, v115
	v_cvt_pk_bf16_f32 v66, v70, v71
	v_lshlrev_b32_e32 v146, 16, v66
	v_cndmask_b32_e32 v69, 0, v69, vcc
	v_cmp_lt_i32_e32 vcc, v152, v116
	v_and_b32_e32 v147, 0xffff0000, v66
	v_exp_f32_e32 v144, v144
	v_cndmask_b32_e32 v68, 0, v68, vcc
	v_cvt_pk_bf16_f32 v67, v68, v69
	v_exp_f32_e32 v145, v145
	v_pk_add_f32 v[70:71], v[70:71], v[146:147] neg_lo:[0,1] neg_hi:[0,1]
	v_lshlrev_b32_e32 v146, 16, v67
	v_and_b32_e32 v147, 0xffff0000, v67
	v_pk_add_f32 v[68:69], v[68:69], v[146:147] neg_lo:[0,1] neg_hi:[0,1]
	v_or_b32_e32 v146, 9, v0
	v_cvt_pk_bf16_f32 v70, v70, v71
	v_cvt_pk_bf16_f32 v71, v68, v69
	v_or_b32_e32 v147, 8, v0
	v_pk_mul_f32 v[68:69], v[122:123], v[72:73]
	v_cmp_lt_i32_e32 vcc, v146, v115
	v_pk_mul_f32 v[144:145], v[122:123], v[144:145]
	s_nop 0
	v_cndmask_b32_e32 v73, 0, v69, vcc
	v_cmp_lt_i32_e32 vcc, v147, v116
	v_or_b32_e32 v69, 11, v0
	ds_read2_b64 v[146:149], v142 offset1:2
	v_cndmask_b32_e32 v72, 0, v68, vcc
	v_cmp_lt_i32_e32 vcc, v69, v115
	v_cvt_pk_bf16_f32 v68, v72, v73
	v_lshlrev_b32_e32 v154, 16, v68
	v_cndmask_b32_e32 v157, 0, v145, vcc
	v_cmp_lt_i32_e32 vcc, v150, v116
	v_and_b32_e32 v155, 0xffff0000, v68
	v_pk_add_f32 v[72:73], v[72:73], v[154:155] neg_lo:[0,1] neg_hi:[0,1]
	v_cndmask_b32_e32 v156, 0, v144, vcc
	v_add_u32_e32 v144, 0x4000, v142
	ds_read2_b64 v[150:153], v144 offset0:64 offset1:66
	ds_read2_b64 v[250:253], v142 offset0:4 offset1:6
	v_cvt_pk_bf16_f32 v69, v156, v157
	v_cvt_pk_bf16_f32 v72, v72, v73
	s_and_b64 vcc, exec, s[8:9]
	s_waitcnt lgkmcnt(1)
	v_mfma_f32_32x32x16_bf16 v[34:49], v[146:149], v[66:69], v[34:49]
	v_lshlrev_b32_e32 v146, 16, v69
	v_and_b32_e32 v147, 0xffff0000, v69
	v_add_f32_e64 v146, v156, -v146
	v_add_f32_e64 v147, v157, -v147
	v_cvt_pk_bf16_f32 v73, v146, v147
	s_waitcnt lgkmcnt(0)
	v_mfma_f32_32x32x16_bf16 v[50:65], v[150:153], v[66:69], v[50:65]
	s_cbranch_vccz .LBB0_441
	v_cmp_eq_u32_e32 vcc, v131, v0
	v_add_u32_e32 v146, 1, v143
	v_cmp_gt_i32_e64 s[6:7], 3, v146
	v_cndmask_b32_e32 v145, 0, v207, vcc
	v_cmp_lt_i32_e32 vcc, -1, v143
	s_and_b64 s[6:7], vcc, s[6:7]
	v_add_u32_e32 v147, 2, v143
	v_cndmask_b32_e64 v146, 0, v207, s[6:7]
	v_cmp_gt_i32_e64 s[6:7], 3, v147
	s_and_b64 vcc, vcc, s[6:7]
	v_add_u32_e32 v148, 4, v143
	v_cndmask_b32_e32 v147, 0, v207, vcc
	v_cmp_gt_u32_e32 vcc, 8, v148
	v_add_u32_e32 v149, 9, v143
	v_cmp_gt_i32_e64 s[6:7], 3, v149
	v_cndmask_b32_e32 v150, 0, v208, vcc
	v_cmp_eq_u32_e32 vcc, v133, v0
	v_add_u32_e32 v149, 10, v143
	v_add_u32_e32 v152, 12, v143
	v_cndmask_b32_e32 v148, 0, v207, vcc
	v_cmp_lt_i32_e32 vcc, -9, v143
	s_and_b64 s[6:7], vcc, s[6:7]
	v_cndmask_b32_e64 v151, 0, v207, s[6:7]
	v_cmp_gt_i32_e64 s[6:7], 3, v149
	s_and_b64 vcc, vcc, s[6:7]
	v_cndmask_b32_e32 v149, 0, v207, vcc
	v_cmp_gt_u32_e32 vcc, 8, v152
	v_perm_b32 v148, v151, v148, s61
	v_perm_b32 v147, v150, v147, s61
	v_cndmask_b32_e32 v152, 0, v208, vcc
	v_perm_b32 v149, v152, v149, s61
	v_perm_b32 v146, v146, v145, s61
	s_nop 1
	v_mfma_f32_32x32x16_bf16 v[18:33], v[146:149], v[66:69], v[18:33]
	v_mfma_f32_32x32x16_bf16 v[18:33], v[146:149], v[70:73], v[18:33]

; DI unsigned pack2(float a, float b) { f32x2 v = {a, b}; bf16x2_t r = __builtin_convertvector(v, bf16x2_t); return __builtin_bit_cast(unsigned, r); }
; DI float bflo(unsigned v) { return __uint_as_float(v << 16); }
; DI float bfhi(unsigned v) { return __uint_as_float(v & 0xffff0000u); }
; DI f32x16 mfma32(bf16x8 a, bf16x8 b, f32x16 c) { return __builtin_amdgcn_mfma_f32_32x32x16_bf16(a, b, c, 0, 0, 0); }
; DI void nsa_cmp_unit(const Params& p, int u, char* smem) {
;     ...
;       for (int st = 0; st < 2; ++st) {
;         u32x4 ph, pl;
; #pragma unroll
;         for (int e = 0; e < 4; ++e) {
;           const float a0 = s[8 * st + 2 * e], a1 = s[8 * st + 2 * e + 1];
;           const unsigned hw = pack2(a0, a1); ph[e] = hw; pl[e] = pack2(a0 - bflo(hw), a1 - bfhi(hw));
;         }
;         const bf16x8 pbh = __builtin_bit_cast(bf16x8, ph), pbl = __builtin_bit_cast(bf16x8, pl);
; #pragma unroll
;         for (int dt = 0; dt < 2; ++dt) {
;           const s16x4 lo = *(const s16x4*)(Vc + (32 * dt + r) * VSTR + 32 * T + 16 * st + 4 * h);
;           const s16x4 hi = *(const s16x4*)(Vc + (32 * dt + r) * VSTR + 32 * T + 16 * st + 8 + 4 * h);
;           o[dt] = mfma32(__builtin_shufflevector(lo, hi, 0, 1, 2, 3, 4, 5, 6, 7), pbh, o[dt]);
;         }
; #pragma unroll
;         for (int jt = 0; jt < 2; ++jt) {
;           if ((jt == 0 && T <= 3) || (jt == 1 && T >= 3)) {
;             const int base = 32 * T + 16 * st + 4 * h - 128 * jt - 4 * r;
;             bf16x8 ov;
; #pragma unroll
;             for (int jj = 0; jj < 8; ++jj) {
;               const int d = base + 8 * (jj >> 2) + (jj & 3);
;               ov[jj] = (short)((d == -1 || d == 3) ? 0x3F00 : ((d >= 0 && d <= 2) ? 0x3F80 : 0));
;             }
;             imp[jt] = mfma32(ov, pbh, imp[jt]);
;             imp[jt] = mfma32(ov, pbl, imp[jt]);
;           }
.LBB0_443:
	v_sub_f32_e32 v66, v74, v140
	v_sub_f32_e32 v67, v75, v140
	v_mul_f32_e32 v66, 0x3fb8aa3b, v66
	v_mul_f32_e32 v67, 0x3fb8aa3b, v67
	v_exp_f32_e32 v66, v66
	v_exp_f32_e32 v67, v67
	v_sub_f32_e32 v68, v76, v140
	v_sub_f32_e32 v69, v77, v140
	v_mul_f32_e32 v68, 0x3fb8aa3b, v68
	v_mul_f32_e32 v69, 0x3fb8aa3b, v69
	v_sub_f32_e32 v70, v78, v140
	v_sub_f32_e32 v71, v79, v140
	v_exp_f32_e32 v68, v68
	v_exp_f32_e32 v69, v69
	v_mul_f32_e32 v70, 0x3fb8aa3b, v70
	v_mul_f32_e32 v71, 0x3fb8aa3b, v71
	v_sub_f32_e32 v72, v80, v140
	v_sub_f32_e32 v73, v81, v140
	v_exp_f32_e32 v70, v70
	v_exp_f32_e32 v71, v71
	v_mul_f32_e32 v72, 0x3fb8aa3b, v72
	v_mul_f32_e32 v73, 0x3fb8aa3b, v73
	v_or_b32_e32 v74, 17, v117
	v_or_b32_e32 v75, 16, v0
	v_pk_mul_f32 v[66:67], v[122:123], v[66:67]
	v_exp_f32_e32 v72, v72
	v_exp_f32_e32 v73, v73
	v_cmp_lt_i32_e32 vcc, v75, v116
	v_cmp_lt_i32_e64 s[6:7], v74, v115
	v_pk_mul_f32 v[68:69], v[122:123], v[68:69]
	v_cndmask_b32_e32 v74, 0, v66, vcc
	v_cndmask_b32_e64 v75, 0, v67, s[6:7]
	v_or_b32_e32 v66, 19, v117
	v_or_b32_e32 v67, 18, v0
	v_cmp_lt_i32_e32 vcc, v67, v116
	v_cmp_lt_i32_e64 s[6:7], v66, v115
	v_or_b32_e32 v66, 25, v117
	v_or_b32_e32 v67, 24, v0
	v_pk_mul_f32 v[70:71], v[122:123], v[70:71]
	v_cndmask_b32_e64 v69, 0, v69, s[6:7]
	v_cndmask_b32_e32 v68, 0, v68, vcc
	v_cmp_lt_i32_e32 vcc, v67, v116
	v_cmp_lt_i32_e64 s[6:7], v66, v115
	v_or_b32_e32 v66, 27, v117
	v_or_b32_e32 v67, 26, v0
	v_pk_mul_f32 v[72:73], v[122:123], v[72:73]
	v_cndmask_b32_e64 v77, 0, v71, s[6:7]
	v_cndmask_b32_e32 v76, 0, v70, vcc
	v_cmp_lt_i32_e32 vcc, v67, v116
	v_cmp_lt_i32_e64 s[6:7], v66, v115
	v_cvt_pk_bf16_f32 v66, v74, v75
	v_cvt_pk_bf16_f32 v67, v68, v69
	v_cndmask_b32_e64 v79, 0, v73, s[6:7]
	v_cndmask_b32_e32 v78, 0, v72, vcc
	v_lshlrev_b32_e32 v70, 16, v66
	v_and_b32_e32 v71, 0xffff0000, v66
	v_lshlrev_b32_e32 v72, 16, v67
	v_and_b32_e32 v73, 0xffff0000, v67
	v_pk_add_f32 v[70:71], v[74:75], v[70:71] neg_lo:[0,1] neg_hi:[0,1]
	v_pk_add_f32 v[68:69], v[68:69], v[72:73] neg_lo:[0,1] neg_hi:[0,1]
	v_cvt_pk_bf16_f32 v70, v70, v71
	v_cvt_pk_bf16_f32 v71, v68, v69
	v_cvt_pk_bf16_f32 v68, v76, v77
	v_cvt_pk_bf16_f32 v69, v78, v79
	v_lshlrev_b32_e32 v72, 16, v68
	v_and_b32_e32 v73, 0xffff0000, v68
	v_lshlrev_b32_e32 v74, 16, v69
	v_and_b32_e32 v75, 0xffff0000, v69
	v_pk_add_f32 v[72:73], v[76:77], v[72:73] neg_lo:[0,1] neg_hi:[0,1]
	v_pk_add_f32 v[74:75], v[78:79], v[74:75] neg_lo:[0,1] neg_hi:[0,1]
	v_cvt_pk_bf16_f32 v72, v72, v73
	v_cvt_pk_bf16_f32 v73, v74, v75
	ds_read2_b64 v[74:77], v144 offset0:68 offset1:70
	s_waitcnt lgkmcnt(1)
	v_mfma_f32_32x32x16_bf16 v[34:49], v[250:253], v[66:69], v[34:49]
	s_andn2_b64 vcc, exec, s[8:9]
	s_waitcnt lgkmcnt(0)
	v_mfma_f32_32x32x16_bf16 v[50:65], v[74:77], v[66:69], v[50:65]
	s_cbranch_vccnz .LBB0_445
	v_cmp_eq_u32_e32 vcc, v137, v0
	v_add_u32_e32 v75, 17, v143
	s_movk_i32 s6, 0xffef
	v_cndmask_b32_e32 v74, 0, v207, vcc
	v_cmp_lt_i32_e32 vcc, s6, v143
	v_cmp_gt_i32_e64 s[6:7], 3, v75
	s_and_b64 s[6:7], vcc, s[6:7]
	v_add_u32_e32 v75, 18, v143
	v_cndmask_b32_e64 v78, 0, v207, s[6:7]
	v_cmp_gt_i32_e64 s[6:7], 3, v75
	s_and_b64 vcc, vcc, s[6:7]
	v_add_u32_e32 v76, 20, v143
	v_cndmask_b32_e32 v75, 0, v207, vcc
	v_cmp_gt_u32_e32 vcc, 8, v76
	v_add_u32_e32 v77, 25, v143
	s_movk_i32 s6, 0xffe7
	v_cndmask_b32_e32 v79, 0, v208, vcc
	v_cmp_eq_u32_e32 vcc, v136, v0
	v_add_u32_e32 v81, 28, v143
	v_perm_b32 v75, v79, v75, s61
	v_cndmask_b32_e32 v76, 0, v207, vcc
	v_cmp_lt_i32_e32 vcc, s6, v143
	v_cmp_gt_i32_e64 s[6:7], 3, v77
	s_and_b64 s[6:7], vcc, s[6:7]
	v_add_u32_e32 v77, 26, v143
	v_cndmask_b32_e64 v80, 0, v207, s[6:7]
	v_cmp_gt_i32_e64 s[6:7], 3, v77
	s_and_b64 vcc, vcc, s[6:7]
	v_cndmask_b32_e32 v77, 0, v207, vcc
	v_cmp_gt_u32_e32 vcc, 8, v81
	v_perm_b32 v76, v80, v76, s61
	v_perm_b32 v74, v78, v74, s61
	v_cndmask_b32_e32 v81, 0, v208, vcc
	v_perm_b32 v77, v81, v77, s61
	s_nop 1
	v_mfma_f32_32x32x16_bf16 v[18:33], v[74:77], v[66:69], v[18:33]
	v_mfma_f32_32x32x16_bf16 v[18:33], v[74:77], v[70:73], v[18:33]
